# retention output: gate rows loaded at the start of the S_fut/PV section (into free registers) so their HBM latency is hidden; group-norm reductions interleaved
# speedup vs baseline: 1.0009x; 1.0009x over previous
.LBB0_802:
	s_and_b32 s12, s11, 3
	v_cvt_f32_ubyte0_e32 v0, s12
	v_sub_f32_e32 v0, 0xc0a00000, v0
	v_cmp_gt_f32_e32 vcc, s20, v0
	s_ashr_i32 s8, s11, 6
	s_ashr_i32 s9, s8, 31
	v_cndmask_b32_e32 v1, 0, v228, vcc
	v_add_f32_e32 v0, v0, v1
	s_lshl_b64 s[0:1], s[8:9], 11
	s_and_b32 s13, s10, 0x780
	v_exp_f32_e32 v0, v0
	s_or_b32 s0, s0, s13
	s_and_b64 s[14:15], vcc, exec
	s_cselect_b32 s9, 0xffffffc0, 0
	v_ldexp_f32 v16, v0, s9
	v_sub_f32_e32 v2, 1.0, v16
	v_add_f32_e32 v0, -1.0, v2
	v_sub_f32_e32 v1, v0, v2
	v_add_f32_e32 v1, 1.0, v1
	v_sub_f32_e64 v0, -v16, v0
	v_add_f32_e32 v3, v0, v1
	v_frexp_mant_f32_e32 v0, v2
	v_cmp_gt_f32_e32 vcc, s17, v0
	v_cvt_f64_f32_e32 v[0:1], v2
	v_frexp_exp_i32_f64_e32 v0, v[0:1]
	v_subbrev_co_u32_e32 v8, vcc, 0, v0, vcc
	v_sub_u32_e32 v0, 0, v8
	v_ldexp_f32 v1, v2, v0
	v_add_f32_e32 v2, -1.0, v1
	v_add_f32_e32 v4, 1.0, v1
	v_ldexp_f32 v0, v3, v0
	v_add_f32_e32 v3, 1.0, v2
	v_add_f32_e32 v5, -1.0, v4
	v_sub_f32_e32 v3, v1, v3
	v_sub_f32_e32 v1, v1, v5
	v_add_f32_e32 v3, v0, v3
	v_add_f32_e32 v0, v0, v1
	v_add_f32_e32 v9, v4, v0
	v_rcp_f32_e32 v11, v9
	v_sub_f32_e32 v1, v9, v4
	v_sub_f32_e32 v10, v0, v1
	v_add_f32_e32 v1, v2, v3
	v_mul_f32_e32 v13, v1, v11
	v_sub_f32_e32 v0, v1, v2
	v_mul_f32_e32 v2, v9, v13
	v_fma_f32 v4, v13, v9, -v2
	v_fmac_f32_e32 v4, v13, v10
	v_sub_f32_e32 v12, v3, v0
	v_add_f32_e32 v0, v2, v4
	v_sub_f32_e32 v3, v1, v0
	v_pk_add_f32 v[6:7], v[0:1], v[2:3] neg_lo:[0,1] neg_hi:[0,1]
	v_mov_b32_e32 v5, v0
	v_pk_add_f32 v[0:1], v[6:7], v[4:5] neg_lo:[0,1] neg_hi:[0,1]
	v_cmp_nlt_f32_e32 vcc, 1.0, v16
	v_add_f32_e32 v1, v12, v1
	v_add_f32_e32 v0, v0, v1
	v_add_f32_e32 v1, v3, v0
	v_mul_f32_e32 v12, v11, v1
	v_mul_f32_e32 v2, v9, v12
	v_fma_f32 v4, v12, v9, -v2
	v_fmac_f32_e32 v4, v12, v10
	v_sub_f32_e32 v3, v3, v1
	v_add_f32_e32 v9, v0, v3
	v_add_f32_e32 v0, v2, v4
	v_sub_f32_e32 v3, v1, v0
	v_pk_add_f32 v[6:7], v[0:1], v[2:3] neg_lo:[0,1] neg_hi:[0,1]
	v_mov_b32_e32 v5, v0
	v_pk_add_f32 v[0:1], v[6:7], v[4:5] neg_lo:[0,1] neg_hi:[0,1]
	v_mov_b64_e32 v[98:99], s[6:7]
	v_add_f32_e32 v1, v9, v1
	v_add_f32_e32 v0, v0, v1
	v_add_f32_e32 v1, v13, v12
	v_add_f32_e32 v0, v3, v0
	v_sub_f32_e32 v2, v1, v13
	v_mul_f32_e32 v0, v11, v0
	v_sub_f32_e32 v2, v12, v2
	v_add_f32_e32 v2, v2, v0
	v_add_f32_e32 v4, v1, v2
	v_mul_f32_e32 v5, v4, v4
	v_fmamk_f32 v0, v5, 0x3e9b6dac, v222
	v_fmaak_f32 v185, v5, v0, 0x3f2aaada
	v_cvt_f32_i32_e32 v0, v8
	v_sub_f32_e32 v1, v4, v1
	v_sub_f32_e32 v1, v2, v1
	v_ldexp_f32 v6, v1, 1
	v_mul_f32_e32 v1, v4, v5
	v_ldexp_f32 v3, v4, 1
	v_pk_mul_f32 v[4:5], v[0:1], v[184:185]
	s_lshl_b32 s88, s12, 8
	v_fma_f32 v2, v0, s23, -v4
	v_fmac_f32_e32 v2, 0xb102e308, v0
	v_pk_add_f32 v[0:1], v[4:5], v[2:3]
	v_add_u32_e32 v185, 0, v100
	v_sub_f32_e32 v3, v1, v3
	v_sub_f32_e32 v3, v5, v3
	v_add_f32_e32 v7, v6, v3
	v_mov_b32_e32 v6, v4
	v_pk_add_f32 v[4:5], v[0:1], v[4:5] neg_lo:[0,1] neg_hi:[0,1]
	v_pk_add_f32 v[8:9], v[0:1], v[6:7]
	v_mov_b32_e32 v3, v0
	v_mov_b32_e32 v5, v9
	v_pk_add_f32 v[10:11], v[2:3], v[4:5] neg_lo:[0,1] neg_hi:[0,1]
	v_pk_add_f32 v[2:3], v[2:3], v[4:5]
	v_mov_b32_e32 v14, v1
	v_pk_add_f32 v[4:5], v[2:3], v[0:1] op_sel:[1,0] op_sel_hi:[0,1] neg_lo:[0,1] neg_hi:[0,1]
	v_pk_add_f32 v[12:13], v[8:9], v[4:5] op_sel_hi:[1,0] neg_lo:[0,1] neg_hi:[0,1]
	v_mov_b32_e32 v8, v9
	v_mov_b32_e32 v9, v3
	v_mov_b32_e32 v15, v4
	v_pk_add_f32 v[4:5], v[8:9], v[14:15] neg_lo:[0,1] neg_hi:[0,1]
	v_mov_b32_e32 v6, v7
	v_mov_b32_e32 v7, v0
	v_pk_add_f32 v[0:1], v[6:7], v[4:5] neg_lo:[0,1] neg_hi:[0,1]
	v_mov_b32_e32 v12, v10
	v_pk_add_f32 v[4:5], v[12:13], v[0:1]
	v_mov_b32_e32 v11, v3
	v_pk_add_f32 v[6:7], v[4:5], v[4:5] op_sel:[0,1] op_sel_hi:[1,0]
	s_lshl_b32 s8, s8, 2
	v_pk_add_f32 v[2:3], v[2:3], v[6:7] op_sel:[1,0] op_sel_hi:[0,1]
	v_mov_b32_e32 v5, v2
	v_pk_add_f32 v[8:9], v[4:5], v[10:11] neg_lo:[0,1] neg_hi:[0,1]
	v_mov_b32_e32 v1, v6
	v_sub_f32_e32 v3, v4, v8
	v_pk_add_f32 v[0:1], v[0:1], v[8:9] neg_lo:[0,1] neg_hi:[0,1]
	v_sub_f32_e32 v3, v10, v3
	v_add_f32_e32 v0, v0, v3
	v_add_f32_e32 v0, v0, v1
	v_add_f32_e32 v0, v2, v0
	v_cndmask_b32_e32 v0, v225, v0, vcc
	v_cmp_neq_f32_e32 vcc, 1.0, v16
	s_or_b32 s8, s8, s12
	v_add_u32_e32 v197, 0, v101
	v_cndmask_b32_e32 v0, v229, v0, vcc
	v_cmp_gt_f32_e32 vcc, s25, v16
	s_ashr_i32 s9, s8, 31
	v_add_u32_e32 v198, 0, v102
	v_cndmask_b32_e64 v200, v0, -v16, vcc
	v_lshl_add_u64 v[0:1], s[0:1], 0, v[82:83]
	v_mad_u64_u32 v[2:3], s[14:15], v0, s97, v[98:99]
	v_mad_i32_i24 v3, v1, s97, v3
	v_lshl_add_u64 v[0:1], v[2:3], 0, s[88:89]
	v_lshl_add_u64 v[0:1], v[0:1], 0, v[32:33]
	v_add_co_u32_e32 v2, vcc, s93, v0
	s_lshl_b64 s[8:9], s[8:9], 11
	s_nop 0
	v_addc_co_u32_e32 v3, vcc, 0, v1, vcc
	v_add_co_u32_e32 v0, vcc, s96, v0
	global_load_dwordx4 v[42:45], v[2:3], off offset:3072
	s_nop 0
	v_addc_co_u32_e32 v1, vcc, 0, v1, vcc
	global_load_dwordx4 v[46:49], v[0:1], off
	global_load_dwordx4 v[28:31], v[0:1], off offset:1024
	v_lshl_add_u64 v[0:1], s[0:1], 0, v[92:93]
	v_mad_u64_u32 v[2:3], s[14:15], v0, s97, v[98:99]
	v_mad_i32_i24 v3, v1, s97, v3
	v_lshl_add_u64 v[0:1], v[2:3], 0, s[88:89]
	v_lshl_add_u64 v[0:1], v[0:1], 0, v[32:33]
	v_add_co_u32_e32 v2, vcc, s93, v0
	v_add_u32_e32 v199, 0, v103
	s_nop 0
	v_addc_co_u32_e32 v3, vcc, 0, v1, vcc
	v_add_co_u32_e32 v0, vcc, s96, v0
	global_load_dwordx4 v[34:37], v[2:3], off offset:3072
	s_nop 0
	v_addc_co_u32_e32 v1, vcc, 0, v1, vcc
	global_load_dwordx4 v[38:41], v[0:1], off
	global_load_dwordx4 v[16:19], v[0:1], off offset:1024
	v_lshl_add_u64 v[0:1], s[0:1], 0, v[94:95]
	v_mad_u64_u32 v[2:3], s[14:15], v0, s97, v[98:99]
	v_mad_i32_i24 v3, v1, s97, v3
	v_lshl_add_u64 v[0:1], v[2:3], 0, s[88:89]
	v_lshl_add_u64 v[0:1], v[0:1], 0, v[32:33]
	v_add_co_u32_e32 v2, vcc, s93, v0
	s_or_b32 s8, s8, s13
	s_nop 0
	v_addc_co_u32_e32 v3, vcc, 0, v1, vcc
	v_add_co_u32_e32 v0, vcc, s96, v0
	global_load_dwordx4 v[20:23], v[2:3], off offset:3072
	s_nop 0
	v_addc_co_u32_e32 v1, vcc, 0, v1, vcc
	global_load_dwordx4 v[24:27], v[0:1], off
	global_load_dwordx4 v[4:7], v[0:1], off offset:1024
	v_lshl_add_u64 v[0:1], s[0:1], 0, v[96:97]
	v_mad_u64_u32 v[2:3], s[14:15], v0, s97, v[98:99]
	v_mad_i32_i24 v3, v1, s97, v3
	v_lshl_add_u64 v[0:1], v[2:3], 0, s[88:89]
	v_lshl_add_u64 v[0:1], v[0:1], 0, v[32:33]
	v_add_co_u32_e32 v2, vcc, s93, v0
	v_mul_f32_e32 v200, 0x3fb8aa3b, v200
	s_nop 0
	v_addc_co_u32_e32 v3, vcc, 0, v1, vcc
	v_add_co_u32_e32 v0, vcc, s96, v0
	global_load_dwordx4 v[8:11], v[2:3], off offset:3072
	s_nop 0
	v_addc_co_u32_e32 v1, vcc, 0, v1, vcc
	global_load_dwordx4 v[12:15], v[0:1], off
	s_nop 0
	global_load_dwordx4 v[0:3], v[0:1], off offset:1024
	s_barrier
	s_waitcnt vmcnt(11)
	ds_write_b128 v185, v[42:45]
	s_waitcnt vmcnt(10)
	ds_write_b128 v185, v[46:49] offset:34816
	v_add_u32_e32 v42, s22, v100
	s_waitcnt vmcnt(9)
	ds_write_b128 v42, v[28:31]
	v_add_u32_e32 v28, s22, v101
	s_waitcnt vmcnt(8)
	ds_write_b128 v197, v[34:37]
	s_waitcnt vmcnt(7)
	ds_write_b128 v197, v[38:41] offset:34816
	s_waitcnt vmcnt(6)
	ds_write_b128 v28, v[16:19]
	v_add_u32_e32 v16, s22, v102
	s_waitcnt vmcnt(5)
	ds_write_b128 v198, v[20:23]
	s_waitcnt vmcnt(4)
	ds_write_b128 v198, v[24:27] offset:34816
	s_waitcnt vmcnt(3)
	ds_write_b128 v16, v[4:7]
	v_add_u32_e32 v4, s22, v103
	s_waitcnt vmcnt(2)
	ds_write_b128 v199, v[8:11]
	s_waitcnt vmcnt(1)
	ds_write_b128 v199, v[12:15] offset:34816
	s_waitcnt vmcnt(0)
	ds_write_b128 v4, v[0:3]
	v_lshl_add_u64 v[0:1], s[8:9], 0, v[82:83]
	v_lshlrev_b64 v[0:1], 8, v[0:1]
	v_lshl_add_u64 v[2:3], v[84:85], 0, v[0:1]
	v_lshl_add_u64 v[0:1], v[86:87], 0, v[0:1]
	global_load_dwordx4 v[16:19], v[2:3], off
	global_load_dwordx4 v[34:37], v[0:1], off
	v_lshl_add_u64 v[0:1], s[8:9], 0, v[92:93]
	v_lshlrev_b64 v[0:1], 8, v[0:1]
	v_lshl_add_u64 v[2:3], v[84:85], 0, v[0:1]
	v_lshl_add_u64 v[0:1], v[86:87], 0, v[0:1]
	global_load_dwordx4 v[20:23], v[2:3], off
	global_load_dwordx4 v[38:41], v[0:1], off
	v_lshl_add_u64 v[0:1], s[8:9], 0, v[94:95]
	v_lshlrev_b64 v[0:1], 8, v[0:1]
	v_lshl_add_u64 v[2:3], v[84:85], 0, v[0:1]
	v_lshl_add_u64 v[0:1], v[86:87], 0, v[0:1]
	global_load_dwordx4 v[24:27], v[2:3], off
	global_load_dwordx4 v[42:45], v[0:1], off
	v_lshl_add_u64 v[0:1], s[8:9], 0, v[96:97]
	v_lshlrev_b64 v[0:1], 8, v[0:1]
	v_lshl_add_u64 v[2:3], v[84:85], 0, v[0:1]
	v_lshl_add_u64 v[0:1], v[86:87], 0, v[0:1]
	global_load_dwordx4 v[28:31], v[2:3], off
	global_load_dwordx4 v[78:81], v[0:1], off
	s_waitcnt lgkmcnt(0)
	s_barrier
	ds_read_b128 v[74:77], v173
	ds_read_b128 v[70:73], v173 offset:32
	ds_read_b128 v[66:69], v173 offset:64
	ds_read_b128 v[62:65], v173 offset:96
	ds_read_b128 v[58:61], v173 offset:128
	ds_read_b128 v[54:57], v173 offset:160
	ds_read_b128 v[50:53], v173 offset:192
	ds_read_b128 v[46:49], v173 offset:224
	ds_read_b128 v[0:3], v174 offset:34816
	ds_read_b128 v[202:205], v174 offset:34848
	s_waitcnt lgkmcnt(1)
	v_mfma_f32_32x32x16_bf16 v[0:15], v[0:3], v[74:77], 0
	v_mul_f32_e32 v201, v200, v104
	v_exp_f32_e32 v201, v201
	s_lshl_b32 s8, s12, 9
	s_mov_b32 s9, s89
	s_add_i32 s11, s11, s28
	s_add_i32 s10, s10, s16
	s_cmpk_lt_i32 s11, 0x400
	s_waitcnt lgkmcnt(0)
	v_mfma_f32_32x32x16_bf16 v[0:15], v[202:205], v[70:73], v[0:15]
	ds_read_b128 v[202:205], v174 offset:34880
	s_waitcnt lgkmcnt(0)
	v_mfma_f32_32x32x16_bf16 v[0:15], v[202:205], v[66:69], v[0:15]
	ds_read_b128 v[202:205], v174 offset:34912
	s_waitcnt lgkmcnt(0)
	v_mfma_f32_32x32x16_bf16 v[0:15], v[202:205], v[62:65], v[0:15]
	ds_read_b128 v[202:205], v174 offset:34944
	s_waitcnt lgkmcnt(0)
	v_mfma_f32_32x32x16_bf16 v[0:15], v[202:205], v[58:61], v[0:15]
	ds_read_b128 v[202:205], v174 offset:34976
	s_waitcnt lgkmcnt(0)
	v_mfma_f32_32x32x16_bf16 v[0:15], v[202:205], v[54:57], v[0:15]
	ds_read_b128 v[202:205], v174 offset:35008
	s_waitcnt lgkmcnt(0)
	v_mfma_f32_32x32x16_bf16 v[0:15], v[202:205], v[50:53], v[0:15]
	ds_read_b128 v[202:205], v174 offset:35040
	s_waitcnt lgkmcnt(0)
	v_mfma_f32_32x32x16_bf16 v[0:15], v[202:205], v[46:49], v[0:15]
	s_nop 11
	v_mul_f32_e32 v0, v0, v201
	v_mul_f32_e32 v201, v200, v105
	v_exp_f32_e32 v201, v201
	s_nop 0
	v_mul_f32_e32 v1, v1, v201
	v_mul_f32_e32 v201, v200, v106
	v_exp_f32_e32 v201, v201
	v_cvt_pk_bf16_f32 v0, v0, v1
	s_nop 0
	v_mul_f32_e32 v2, v2, v201
	v_mul_f32_e32 v201, v200, v107
	v_exp_f32_e32 v201, v201
	s_nop 0
	v_mul_f32_e32 v3, v3, v201
	v_cvt_pk_bf16_f32 v1, v2, v3
	ds_write_b64 v177, v[0:1]
	v_mul_f32_e32 v0, v200, v108
	v_mul_f32_e32 v1, v200, v109
	v_exp_f32_e32 v0, v0
	v_exp_f32_e32 v1, v1
	v_mul_f32_e32 v2, v200, v110
	v_mul_f32_e32 v3, v200, v111
	v_exp_f32_e32 v2, v2
	v_exp_f32_e32 v3, v3
	v_mul_f32_e32 v0, v4, v0
	v_mul_f32_e32 v1, v5, v1
	v_mul_f32_e32 v2, v6, v2
	v_mul_f32_e32 v3, v7, v3
	v_cvt_pk_bf16_f32 v0, v0, v1
	v_cvt_pk_bf16_f32 v1, v2, v3
	ds_write_b64 v190, v[0:1]
	v_mul_f32_e32 v0, v200, v112
	v_mul_f32_e32 v1, v200, v113
	v_exp_f32_e32 v0, v0
	v_exp_f32_e32 v1, v1
	v_mul_f32_e32 v2, v200, v114
	v_mul_f32_e32 v3, v200, v115
	v_exp_f32_e32 v2, v2
	v_exp_f32_e32 v3, v3
	v_mul_f32_e32 v0, v8, v0
	v_mul_f32_e32 v1, v9, v1
	v_mul_f32_e32 v2, v10, v2
	v_mul_f32_e32 v3, v11, v3
	v_cvt_pk_bf16_f32 v0, v0, v1
	v_cvt_pk_bf16_f32 v1, v2, v3
	ds_write_b64 v191, v[0:1]
	v_mul_f32_e32 v0, v200, v116
	v_mul_f32_e32 v1, v200, v117
	v_exp_f32_e32 v0, v0
	v_exp_f32_e32 v1, v1
	v_mul_f32_e32 v2, v200, v118
	v_mul_f32_e32 v3, v200, v119
	v_exp_f32_e32 v2, v2
	v_exp_f32_e32 v3, v3
	v_mul_f32_e32 v0, v12, v0
	v_mul_f32_e32 v1, v13, v1
	v_mul_f32_e32 v2, v14, v2
	v_mul_f32_e32 v3, v15, v3
	v_cvt_pk_bf16_f32 v0, v0, v1
	v_cvt_pk_bf16_f32 v1, v2, v3
	ds_write_b64 v192, v[0:1]
	ds_read_b128 v[0:3], v174 offset:43520
	ds_read_b128 v[202:205], v174 offset:43552
	s_waitcnt lgkmcnt(1)
	v_mfma_f32_32x32x16_bf16 v[0:15], v[0:3], v[74:77], 0
	v_mul_f32_e32 v201, v200, v120
	v_exp_f32_e32 v201, v201
	s_waitcnt lgkmcnt(0)
	v_mfma_f32_32x32x16_bf16 v[0:15], v[202:205], v[70:73], v[0:15]
	ds_read_b128 v[202:205], v174 offset:43584
	s_waitcnt lgkmcnt(0)
	v_mfma_f32_32x32x16_bf16 v[0:15], v[202:205], v[66:69], v[0:15]
	ds_read_b128 v[202:205], v174 offset:43616
	s_waitcnt lgkmcnt(0)
	v_mfma_f32_32x32x16_bf16 v[0:15], v[202:205], v[62:65], v[0:15]
	ds_read_b128 v[202:205], v174 offset:43648
	s_waitcnt lgkmcnt(0)
	v_mfma_f32_32x32x16_bf16 v[0:15], v[202:205], v[58:61], v[0:15]
	ds_read_b128 v[202:205], v174 offset:43680
	s_waitcnt lgkmcnt(0)
	v_mfma_f32_32x32x16_bf16 v[0:15], v[202:205], v[54:57], v[0:15]
	ds_read_b128 v[202:205], v174 offset:43712
	s_waitcnt lgkmcnt(0)
	v_mfma_f32_32x32x16_bf16 v[0:15], v[202:205], v[50:53], v[0:15]
	ds_read_b128 v[202:205], v174 offset:43744
	s_waitcnt lgkmcnt(0)
	v_mfma_f32_32x32x16_bf16 v[0:15], v[202:205], v[46:49], v[0:15]
	s_nop 11
	v_mul_f32_e32 v0, v201, v0
	v_mul_f32_e32 v201, v200, v121
	v_exp_f32_e32 v201, v201
	s_nop 0
	v_mul_f32_e32 v1, v201, v1
	v_mul_f32_e32 v201, v200, v122
	v_exp_f32_e32 v201, v201
	v_cvt_pk_bf16_f32 v0, v0, v1
	s_nop 0
	v_mul_f32_e32 v2, v201, v2
	v_mul_f32_e32 v201, v200, v123
	v_exp_f32_e32 v201, v201
	s_nop 0
	v_mul_f32_e32 v3, v201, v3
	v_cvt_pk_bf16_f32 v1, v2, v3
	ds_write_b64 v193, v[0:1]
	v_mul_f32_e32 v0, v200, v124
	v_mul_f32_e32 v1, v200, v125
	v_exp_f32_e32 v0, v0
	v_exp_f32_e32 v1, v1
	v_mul_f32_e32 v2, v200, v126
	v_mul_f32_e32 v3, v200, v127
	v_exp_f32_e32 v2, v2
	v_exp_f32_e32 v3, v3
	v_mul_f32_e32 v0, v0, v4
	v_mul_f32_e32 v1, v1, v5
	v_mul_f32_e32 v2, v2, v6
	v_mul_f32_e32 v3, v3, v7
	v_cvt_pk_bf16_f32 v0, v0, v1
	v_cvt_pk_bf16_f32 v1, v2, v3
	ds_write_b64 v194, v[0:1]
	v_mul_f32_e32 v0, v200, v128
	v_mul_f32_e32 v1, v200, v129
	v_exp_f32_e32 v0, v0
	v_exp_f32_e32 v1, v1
	v_mul_f32_e32 v2, v200, v130
	v_mul_f32_e32 v3, v200, v131
	v_exp_f32_e32 v2, v2
	v_exp_f32_e32 v3, v3
	v_mul_f32_e32 v0, v0, v8
	v_mul_f32_e32 v1, v1, v9
	v_mul_f32_e32 v2, v2, v10
	v_mul_f32_e32 v3, v3, v11
	v_cvt_pk_bf16_f32 v0, v0, v1
	v_cvt_pk_bf16_f32 v1, v2, v3
	ds_write_b64 v195, v[0:1]
	v_mul_f32_e32 v0, v200, v132
	v_mul_f32_e32 v1, v200, v133
	v_exp_f32_e32 v0, v0
	v_exp_f32_e32 v1, v1
	v_mul_f32_e32 v2, v200, v134
	v_mul_f32_e32 v3, v200, v135
	v_exp_f32_e32 v2, v2
	v_exp_f32_e32 v3, v3
	v_mul_f32_e32 v0, v0, v12
	v_mul_f32_e32 v1, v1, v13
	v_mul_f32_e32 v2, v2, v14
	v_mul_f32_e32 v3, v3, v15
	v_cvt_pk_bf16_f32 v0, v0, v1
	v_cvt_pk_bf16_f32 v1, v2, v3
	ds_write_b64 v196, v[0:1]
	s_waitcnt lgkmcnt(0)
	s_barrier
	s_waitcnt vmcnt(7)
	ds_write_b128 v185, v[16:19] offset:34816
	s_waitcnt vmcnt(5)
	ds_write_b128 v197, v[20:23] offset:34816
	s_waitcnt vmcnt(3)
	ds_write_b128 v198, v[24:27] offset:34816
	s_waitcnt vmcnt(1)
	ds_write_b128 v199, v[28:31] offset:34816
	s_waitcnt lgkmcnt(0)
	s_barrier
	ds_read_b128 v[0:3], v174 offset:34816
	ds_read_b128 v[16:19], v174 offset:34848
	s_waitcnt lgkmcnt(1)
	v_mfma_f32_32x32x16_bf16 v[0:15], v[74:77], v[0:3], 0
	ds_read_b128 v[202:205], v174 offset:43552
	v_mul_f32_e32 v201, v200, v136
	v_cmp_gt_f32_e32 vcc, s20, v201
	s_nop 1
	v_cndmask_b32_e32 v201, 0, v228, vcc
	v_fmac_f32_e32 v201, v200, v136
	s_waitcnt lgkmcnt(1)
	v_mfma_f32_32x32x16_bf16 v[0:15], v[70:73], v[16:19], v[0:15]
	ds_read_b128 v[16:19], v174 offset:34880
	v_exp_f32_e32 v201, v201
	s_waitcnt lgkmcnt(0)
	v_mfma_f32_32x32x16_bf16 v[0:15], v[66:69], v[16:19], v[0:15]
	ds_read_b128 v[16:19], v174 offset:34912
	s_waitcnt lgkmcnt(0)
	v_mfma_f32_32x32x16_bf16 v[0:15], v[62:65], v[16:19], v[0:15]
	ds_read_b128 v[16:19], v174 offset:34944
	s_waitcnt lgkmcnt(0)
	v_mfma_f32_32x32x16_bf16 v[0:15], v[58:61], v[16:19], v[0:15]
	ds_read_b128 v[16:19], v174 offset:34976
	s_waitcnt lgkmcnt(0)
	v_mfma_f32_32x32x16_bf16 v[0:15], v[54:57], v[16:19], v[0:15]
	ds_read_b128 v[16:19], v174 offset:35008
	s_waitcnt lgkmcnt(0)
	v_mfma_f32_32x32x16_bf16 v[0:15], v[50:53], v[16:19], v[0:15]
	ds_read_b128 v[16:19], v174 offset:35040
	s_waitcnt lgkmcnt(0)
	v_mfma_f32_32x32x16_bf16 v[0:15], v[46:49], v[16:19], v[0:15]
	ds_read_b128 v[16:19], v174 offset:43520
	s_waitcnt lgkmcnt(0)
	v_mfma_f32_32x32x16_bf16 v[16:31], v[74:77], v[16:19], 0
	v_mfma_f32_32x32x16_bf16 v[16:31], v[70:73], v[202:205], v[16:31]
	ds_read_b128 v[202:205], v174 offset:43584
	s_waitcnt lgkmcnt(0)
	v_mfma_f32_32x32x16_bf16 v[16:31], v[66:69], v[202:205], v[16:31]
	ds_read_b128 v[202:205], v174 offset:43616
	s_waitcnt lgkmcnt(0)
	v_mfma_f32_32x32x16_bf16 v[16:31], v[62:65], v[202:205], v[16:31]
	ds_read_b128 v[202:205], v174 offset:43648
	s_waitcnt lgkmcnt(0)
	v_mfma_f32_32x32x16_bf16 v[16:31], v[58:61], v[202:205], v[16:31]
	ds_read_b128 v[202:205], v174 offset:43680
	s_waitcnt lgkmcnt(0)
	v_mfma_f32_32x32x16_bf16 v[16:31], v[54:57], v[202:205], v[16:31]
	ds_read_b128 v[202:205], v174 offset:43712
	s_waitcnt lgkmcnt(0)
	v_mfma_f32_32x32x16_bf16 v[16:31], v[50:53], v[202:205], v[16:31]
	ds_read_b128 v[202:205], v174 offset:43744
	s_waitcnt lgkmcnt(0)
	s_barrier
	ds_write_b128 v185, v[34:37] offset:34816
	ds_write_b128 v197, v[38:41] offset:34816
	ds_write_b128 v198, v[42:45] offset:34816
	s_waitcnt vmcnt(0)
	ds_write_b128 v199, v[78:81] offset:34816
	s_waitcnt lgkmcnt(0)
	s_barrier
	v_lshl_add_u64 v[252:253], s[0:1], 0, v[90:91]
	v_mad_u64_u32 v[250:251], s[98:99], v252, s97, v[98:99]
	v_mul_lo_u32 v252, v253, s97
	v_add_u32_e32 v251, v251, v252
	v_lshl_add_u64 v[250:251], v[250:251], 0, s[88:89]
	v_lshl_add_u64 v[250:251], v[250:251], 0, v[32:33]
	s_mov_b64 s[98:99], 0x2000
	v_lshl_add_u64 v[242:243], v[250:251], 0, s[98:99]
	global_load_dwordx4 v[242:245], v[242:243], off offset:2048
	s_mov_b64 s[98:99], 0xd000
	v_lshl_add_u64 v[246:247], v[250:251], 0, s[98:99]
	global_load_dwordx4 v[246:249], v[246:247], off offset:2048
	s_mov_b64 s[98:99], 0x18000
	v_lshl_add_u64 v[78:79], v[250:251], 0, s[98:99]
	global_load_dwordx4 v[78:81], v[78:79], off offset:2048
	s_mov_b64 s[98:99], 0x23000
	v_lshl_add_u64 v[250:251], v[250:251], 0, s[98:99]
	global_load_dwordx4 v[250:253], v[250:251], off offset:2048
	v_mfma_f32_32x32x16_bf16 v[16:31], v[46:49], v[202:205], v[16:31]
	v_cndmask_b32_e32 v202, 0, v223, vcc
	v_ldexp_f32 v202, v201, v202
	v_mul_f32_e32 v201, v200, v137
	v_cmp_gt_f32_e32 vcc, s20, v201
	ds_read_b128 v[34:37], v174 offset:34816
	ds_read_b128 v[38:41], v174 offset:34848
	v_cndmask_b32_e32 v201, 0, v228, vcc
	v_fmac_f32_e32 v201, v200, v137
	v_exp_f32_e32 v201, v201
	v_cndmask_b32_e32 v203, 0, v223, vcc
	v_ldexp_f32 v203, v201, v203
	v_mul_f32_e32 v201, v200, v138
	v_cmp_gt_f32_e32 vcc, s20, v201
	v_pk_mul_f32 v[0:1], v[202:203], v[0:1]
	v_pk_mul_f32 v[16:17], v[202:203], v[16:17]
	v_cndmask_b32_e32 v201, 0, v228, vcc
	v_fmac_f32_e32 v201, v200, v138
	v_exp_f32_e32 v201, v201
	v_cndmask_b32_e32 v204, 0, v223, vcc
	v_ldexp_f32 v204, v201, v204
	v_mul_f32_e32 v201, v200, v139
	v_cmp_gt_f32_e32 vcc, s20, v201
	s_nop 1
	v_cndmask_b32_e32 v201, 0, v228, vcc
	v_fmac_f32_e32 v201, v200, v139
	v_exp_f32_e32 v201, v201
	v_cndmask_b32_e32 v205, 0, v223, vcc
	v_ldexp_f32 v205, v201, v205
	v_mul_f32_e32 v201, v200, v140
	v_cmp_gt_f32_e32 vcc, s20, v201
	v_pk_mul_f32 v[2:3], v[204:205], v[2:3]
	v_pk_mul_f32 v[18:19], v[204:205], v[18:19]
	v_cndmask_b32_e32 v201, 0, v228, vcc
	v_fmac_f32_e32 v201, v200, v140
	v_exp_f32_e32 v201, v201
	v_cndmask_b32_e32 v206, 0, v223, vcc
	v_ldexp_f32 v206, v201, v206
	v_mul_f32_e32 v201, v200, v141
	v_cmp_gt_f32_e32 vcc, s20, v201
	s_nop 1
	v_cndmask_b32_e32 v201, 0, v228, vcc
	v_fmac_f32_e32 v201, v200, v141
	v_exp_f32_e32 v201, v201
	v_cndmask_b32_e32 v207, 0, v223, vcc
	v_ldexp_f32 v207, v201, v207
	v_mul_f32_e32 v201, v200, v142
	v_cmp_gt_f32_e32 vcc, s20, v201
	v_pk_mul_f32 v[4:5], v[206:207], v[4:5]
	v_pk_mul_f32 v[20:21], v[206:207], v[20:21]
	v_cndmask_b32_e32 v201, 0, v228, vcc
	v_fmac_f32_e32 v201, v200, v142
	v_exp_f32_e32 v201, v201
	v_cndmask_b32_e32 v208, 0, v223, vcc
	v_ldexp_f32 v208, v201, v208
	v_mul_f32_e32 v201, v200, v143
	v_cmp_gt_f32_e32 vcc, s20, v201
	s_nop 1
	v_cndmask_b32_e32 v201, 0, v228, vcc
	v_fmac_f32_e32 v201, v200, v143
	v_exp_f32_e32 v201, v201
	v_cndmask_b32_e32 v209, 0, v223, vcc
	v_ldexp_f32 v209, v201, v209
	v_mul_f32_e32 v201, v200, v144
	v_cmp_gt_f32_e32 vcc, s20, v201
	v_pk_mul_f32 v[6:7], v[208:209], v[6:7]
	v_pk_mul_f32 v[22:23], v[208:209], v[22:23]
	v_cndmask_b32_e32 v201, 0, v228, vcc
	v_fmac_f32_e32 v201, v200, v144
	v_exp_f32_e32 v201, v201
	v_cndmask_b32_e32 v234, 0, v223, vcc
	v_ldexp_f32 v234, v201, v234
	v_mul_f32_e32 v201, v200, v145
	v_cmp_gt_f32_e32 vcc, s20, v201
	s_nop 1
	v_cndmask_b32_e32 v201, 0, v228, vcc
	v_fmac_f32_e32 v201, v200, v145
	v_exp_f32_e32 v201, v201
	v_cndmask_b32_e32 v235, 0, v223, vcc
	v_ldexp_f32 v235, v201, v235
	v_mul_f32_e32 v201, v200, v146
	v_cmp_gt_f32_e32 vcc, s20, v201
	v_pk_mul_f32 v[8:9], v[234:235], v[8:9]
	v_pk_mul_f32 v[24:25], v[234:235], v[24:25]
	v_cndmask_b32_e32 v201, 0, v228, vcc
	v_fmac_f32_e32 v201, v200, v146
	v_exp_f32_e32 v201, v201
	v_cndmask_b32_e32 v236, 0, v223, vcc
	v_ldexp_f32 v236, v201, v236
	v_mul_f32_e32 v201, v200, v147
	v_cmp_gt_f32_e32 vcc, s20, v201
	s_nop 1
	v_cndmask_b32_e32 v201, 0, v228, vcc
	v_fmac_f32_e32 v201, v200, v147
	v_exp_f32_e32 v201, v201
	v_cndmask_b32_e32 v237, 0, v223, vcc
	v_ldexp_f32 v237, v201, v237
	v_mul_f32_e32 v201, v200, v148
	v_cmp_gt_f32_e32 vcc, s20, v201
	v_pk_mul_f32 v[10:11], v[236:237], v[10:11]
	v_pk_mul_f32 v[26:27], v[236:237], v[26:27]
	v_cndmask_b32_e32 v201, 0, v228, vcc
	v_fmac_f32_e32 v201, v200, v148
	v_exp_f32_e32 v201, v201
	v_cndmask_b32_e32 v238, 0, v223, vcc
	v_ldexp_f32 v238, v201, v238
	v_mul_f32_e32 v201, v200, v149
	v_cmp_gt_f32_e32 vcc, s20, v201
	s_nop 1
	v_cndmask_b32_e32 v201, 0, v228, vcc
	v_fmac_f32_e32 v201, v200, v149
	v_exp_f32_e32 v201, v201
	v_cndmask_b32_e32 v239, 0, v223, vcc
	v_ldexp_f32 v239, v201, v239
	v_mul_f32_e32 v201, v200, v150
	v_cmp_gt_f32_e32 vcc, s20, v201
	v_pk_mul_f32 v[12:13], v[238:239], v[12:13]
	v_pk_mul_f32 v[28:29], v[238:239], v[28:29]
	v_cndmask_b32_e32 v201, 0, v228, vcc
	v_fmac_f32_e32 v201, v200, v150
	v_exp_f32_e32 v201, v201
	v_cndmask_b32_e32 v240, 0, v223, vcc
	v_ldexp_f32 v240, v201, v240
	v_mul_f32_e32 v201, v200, v151
	v_cmp_gt_f32_e32 vcc, s20, v201
	s_nop 1
	v_cndmask_b32_e32 v201, 0, v228, vcc
	v_fmac_f32_e32 v201, v200, v151
	v_exp_f32_e32 v201, v201
	v_cndmask_b32_e32 v241, 0, v223, vcc
	v_ldexp_f32 v241, v201, v241
	v_pk_mul_f32 v[14:15], v[240:241], v[14:15]
	v_pk_mul_f32 v[30:31], v[240:241], v[30:31]
	s_waitcnt lgkmcnt(1)
	v_mfma_f32_32x32x16_bf16 v[0:15], v[74:77], v[34:37], v[0:15]
	ds_read_b128 v[34:37], v174 offset:34880
	s_waitcnt lgkmcnt(1)
	v_mfma_f32_32x32x16_bf16 v[0:15], v[70:73], v[38:41], v[0:15]
	s_waitcnt lgkmcnt(0)
	v_mfma_f32_32x32x16_bf16 v[0:15], v[66:69], v[34:37], v[0:15]
	ds_read_b128 v[34:37], v174 offset:34912
	s_waitcnt lgkmcnt(0)
	v_mfma_f32_32x32x16_bf16 v[0:15], v[62:65], v[34:37], v[0:15]
	ds_read_b128 v[34:37], v174 offset:34944
	s_waitcnt lgkmcnt(0)
	v_mfma_f32_32x32x16_bf16 v[0:15], v[58:61], v[34:37], v[0:15]
	ds_read_b128 v[34:37], v174 offset:34976
	s_waitcnt lgkmcnt(0)
	v_mfma_f32_32x32x16_bf16 v[0:15], v[54:57], v[34:37], v[0:15]
	ds_read_b128 v[34:37], v174 offset:35008
	s_waitcnt lgkmcnt(0)
	v_mfma_f32_32x32x16_bf16 v[0:15], v[50:53], v[34:37], v[0:15]
	ds_read_b128 v[34:37], v174 offset:35040
	s_waitcnt lgkmcnt(0)
	v_mfma_f32_32x32x16_bf16 v[0:15], v[46:49], v[34:37], v[0:15]
	ds_read_b128 v[34:37], v174 offset:43520
	s_waitcnt lgkmcnt(0)
	v_mfma_f32_32x32x16_bf16 v[16:31], v[74:77], v[34:37], v[16:31]
	ds_read_b128 v[34:37], v174 offset:43552
	s_waitcnt lgkmcnt(0)
	v_mfma_f32_32x32x16_bf16 v[16:31], v[70:73], v[34:37], v[16:31]
	ds_read_b128 v[34:37], v174 offset:43584
	s_waitcnt lgkmcnt(0)
	v_mfma_f32_32x32x16_bf16 v[16:31], v[66:69], v[34:37], v[16:31]
	ds_read_b128 v[34:37], v174 offset:43616
	s_waitcnt lgkmcnt(0)
	v_mfma_f32_32x32x16_bf16 v[16:31], v[62:65], v[34:37], v[16:31]
	ds_read_b128 v[34:37], v174 offset:43648
	s_waitcnt lgkmcnt(0)
	v_mfma_f32_32x32x16_bf16 v[16:31], v[58:61], v[34:37], v[16:31]
	ds_read_b128 v[34:37], v174 offset:43680
	s_waitcnt lgkmcnt(0)
	v_mfma_f32_32x32x16_bf16 v[16:31], v[54:57], v[34:37], v[16:31]
	ds_read_b128 v[34:37], v174 offset:43712
	v_add_u32_e32 v54, s92, v169
	s_waitcnt lgkmcnt(0)
	v_mfma_f32_32x32x16_bf16 v[16:31], v[50:53], v[34:37], v[16:31]
	ds_read_b128 v[34:37], v174 offset:43744
	s_waitcnt lgkmcnt(0)
	v_mfma_f32_32x32x16_bf16 v[16:31], v[46:49], v[34:37], v[16:31]
	v_mul_f32_e32 v34, v200, v152
	v_cmp_gt_f32_e32 vcc, s20, v34
	s_nop 1
	v_cndmask_b32_e32 v34, 0, v228, vcc
	v_fmac_f32_e32 v34, v200, v152
	v_exp_f32_e32 v34, v34
	v_cndmask_b32_e32 v35, 0, v223, vcc
	v_ldexp_f32 v34, v34, v35
	v_mul_f32_e32 v35, v200, v153
	v_cmp_gt_f32_e32 vcc, s20, v35
	s_nop 1
	v_cndmask_b32_e32 v35, 0, v228, vcc
	v_fmac_f32_e32 v35, v200, v153
	v_exp_f32_e32 v35, v35
	v_cndmask_b32_e32 v36, 0, v223, vcc
	v_ldexp_f32 v35, v35, v36
	v_mul_f32_e32 v36, v200, v154
	v_cmp_gt_f32_e32 vcc, s20, v36
	v_pk_mul_f32 v[0:1], v[34:35], v[0:1]
	v_pk_mul_f32 v[16:17], v[34:35], v[16:17]
	v_cndmask_b32_e32 v36, 0, v228, vcc
	v_fmac_f32_e32 v36, v200, v154
	v_exp_f32_e32 v36, v36
	v_cndmask_b32_e32 v37, 0, v223, vcc
	v_ldexp_f32 v36, v36, v37
	v_mul_f32_e32 v37, v200, v155
	v_cmp_gt_f32_e32 vcc, s20, v37
	s_nop 1
	v_cndmask_b32_e32 v37, 0, v228, vcc
	v_fmac_f32_e32 v37, v200, v155
	v_exp_f32_e32 v37, v37
	v_cndmask_b32_e32 v38, 0, v223, vcc
	v_ldexp_f32 v37, v37, v38
	v_mul_f32_e32 v38, v200, v156
	v_cmp_gt_f32_e32 vcc, s20, v38
	v_pk_mul_f32 v[2:3], v[36:37], v[2:3]
	v_pk_mul_f32 v[18:19], v[36:37], v[18:19]
	v_cndmask_b32_e32 v38, 0, v228, vcc
	v_fmac_f32_e32 v38, v200, v156
	v_exp_f32_e32 v38, v38
	v_cndmask_b32_e32 v39, 0, v223, vcc
	v_ldexp_f32 v38, v38, v39
	v_mul_f32_e32 v39, v200, v157
	v_cmp_gt_f32_e32 vcc, s20, v39
	s_nop 1
	v_cndmask_b32_e32 v39, 0, v228, vcc
	v_fmac_f32_e32 v39, v200, v157
	v_exp_f32_e32 v39, v39
	v_cndmask_b32_e32 v40, 0, v223, vcc
	v_ldexp_f32 v39, v39, v40
	v_mul_f32_e32 v40, v200, v158
	v_cmp_gt_f32_e32 vcc, s20, v40
	v_pk_mul_f32 v[4:5], v[38:39], v[4:5]
	v_pk_mul_f32 v[20:21], v[38:39], v[20:21]
	v_cndmask_b32_e32 v40, 0, v228, vcc
	v_fmac_f32_e32 v40, v200, v158
	v_exp_f32_e32 v40, v40
	v_cndmask_b32_e32 v41, 0, v223, vcc
	v_ldexp_f32 v40, v40, v41
	v_mul_f32_e32 v41, v200, v159
	v_cmp_gt_f32_e32 vcc, s20, v41
	s_nop 1
	v_cndmask_b32_e32 v41, 0, v228, vcc
	v_fmac_f32_e32 v41, v200, v159
	v_exp_f32_e32 v41, v41
	v_cndmask_b32_e32 v42, 0, v223, vcc
	v_ldexp_f32 v41, v41, v42
	v_mul_f32_e32 v42, v200, v160
	v_cmp_gt_f32_e32 vcc, s20, v42
	v_pk_mul_f32 v[6:7], v[40:41], v[6:7]
	v_pk_mul_f32 v[22:23], v[40:41], v[22:23]
	v_cndmask_b32_e32 v42, 0, v228, vcc
	v_fmac_f32_e32 v42, v200, v160
	v_exp_f32_e32 v42, v42
	v_cndmask_b32_e32 v43, 0, v223, vcc
	v_ldexp_f32 v42, v42, v43
	v_mul_f32_e32 v43, v200, v161
	v_cmp_gt_f32_e32 vcc, s20, v43
	s_nop 1
	v_cndmask_b32_e32 v43, 0, v228, vcc
	v_fmac_f32_e32 v43, v200, v161
	v_exp_f32_e32 v43, v43
	v_cndmask_b32_e32 v44, 0, v223, vcc
	v_ldexp_f32 v43, v43, v44
	v_mul_f32_e32 v44, v200, v162
	v_cmp_gt_f32_e32 vcc, s20, v44
	v_pk_mul_f32 v[8:9], v[42:43], v[8:9]
	v_pk_mul_f32 v[24:25], v[42:43], v[24:25]
	v_cndmask_b32_e32 v44, 0, v228, vcc
	v_fmac_f32_e32 v44, v200, v162
	v_exp_f32_e32 v44, v44
	v_cndmask_b32_e32 v45, 0, v223, vcc
	v_ldexp_f32 v44, v44, v45
	v_mul_f32_e32 v45, v200, v163
	v_cmp_gt_f32_e32 vcc, s20, v45
	s_nop 1
	v_cndmask_b32_e32 v45, 0, v228, vcc
	v_fmac_f32_e32 v45, v200, v163
	v_exp_f32_e32 v45, v45
	v_cndmask_b32_e32 v46, 0, v223, vcc
	v_ldexp_f32 v45, v45, v46
	v_mul_f32_e32 v46, v200, v164
	v_cmp_gt_f32_e32 vcc, s20, v46
	v_pk_mul_f32 v[10:11], v[44:45], v[10:11]
	v_pk_mul_f32 v[26:27], v[44:45], v[26:27]
	v_cndmask_b32_e32 v46, 0, v228, vcc
	v_fmac_f32_e32 v46, v200, v164
	v_exp_f32_e32 v46, v46
	v_cndmask_b32_e32 v47, 0, v223, vcc
	v_ldexp_f32 v46, v46, v47
	v_mul_f32_e32 v47, v200, v165
	v_cmp_gt_f32_e32 vcc, s20, v47
	s_nop 1
	v_cndmask_b32_e32 v47, 0, v228, vcc
	v_fmac_f32_e32 v47, v200, v165
	v_exp_f32_e32 v47, v47
	v_cndmask_b32_e32 v48, 0, v223, vcc
	v_ldexp_f32 v47, v47, v48
	v_mul_f32_e32 v48, v200, v166
	v_cmp_gt_f32_e32 vcc, s20, v48
	v_pk_mul_f32 v[12:13], v[46:47], v[12:13]
	v_pk_mul_f32 v[28:29], v[46:47], v[28:29]
	v_cndmask_b32_e32 v48, 0, v228, vcc
	v_fmac_f32_e32 v48, v200, v166
	v_exp_f32_e32 v48, v48
	v_cndmask_b32_e32 v49, 0, v223, vcc
	v_ldexp_f32 v48, v48, v49
	v_mul_f32_e32 v49, v200, v167
	v_cmp_gt_f32_e32 vcc, s20, v49
	s_nop 1
	v_cndmask_b32_e32 v49, 0, v228, vcc
	v_fmac_f32_e32 v49, v200, v167
	v_exp_f32_e32 v49, v49
	v_cndmask_b32_e32 v50, 0, v223, vcc
	v_ldexp_f32 v49, v49, v50
	v_pk_mul_f32 v[14:15], v[48:49], v[14:15]
	v_pk_mul_f32 v[30:31], v[48:49], v[30:31]
	ds_read_b64_tr_b16 v[46:47], v168 offset:0
	ds_read_b64_tr_b16 v[48:49], v168 offset:1088
	ds_read_b64_tr_b16 v[42:43], v168 offset:64
	ds_read_b64_tr_b16 v[44:45], v168 offset:1152
	ds_read_b64_tr_b16 v[38:39], v168 offset:4352
	ds_read_b64_tr_b16 v[40:41], v168 offset:5440
	ds_read_b64_tr_b16 v[34:35], v168 offset:4416
	ds_read_b64_tr_b16 v[36:37], v168 offset:5504
	s_waitcnt lgkmcnt(0)
	ds_read_b128 v[50:53], v54
	s_waitcnt lgkmcnt(0)
	v_mfma_f32_32x32x16_bf16 v[0:15], v[50:53], v[46:49], v[0:15]
	v_mfma_f32_32x32x16_bf16 v[16:31], v[50:53], v[42:45], v[16:31]
	v_add_u32_e32 v42, 0, v169
	v_add_u32_e32 v55, 0x11020, v42
	ds_read_b128 v[42:45], v55
	s_waitcnt lgkmcnt(0)
	v_mfma_f32_32x32x16_bf16 v[0:15], v[42:45], v[38:41], v[0:15]
	v_mfma_f32_32x32x16_bf16 v[16:31], v[42:45], v[34:37], v[16:31]
	ds_read_b64_tr_b16 v[46:47], v170 offset:0
	ds_read_b64_tr_b16 v[48:49], v170 offset:1088
	ds_read_b64_tr_b16 v[42:43], v170 offset:64
	ds_read_b64_tr_b16 v[44:45], v170 offset:1152
	ds_read_b64_tr_b16 v[38:39], v170 offset:4352
	ds_read_b64_tr_b16 v[40:41], v170 offset:5440
	ds_read_b64_tr_b16 v[34:35], v170 offset:4416
	ds_read_b64_tr_b16 v[36:37], v170 offset:5504
	s_waitcnt lgkmcnt(0)
	ds_read_b128 v[50:53], v54 offset:64
	s_waitcnt lgkmcnt(0)
	v_mfma_f32_32x32x16_bf16 v[16:31], v[50:53], v[42:45], v[16:31]
	ds_read_b128 v[42:45], v55 offset:64
	v_mfma_f32_32x32x16_bf16 v[0:15], v[50:53], v[46:49], v[0:15]
	s_waitcnt lgkmcnt(0)
	v_mfma_f32_32x32x16_bf16 v[0:15], v[42:45], v[38:41], v[0:15]
	v_mfma_f32_32x32x16_bf16 v[16:31], v[42:45], v[34:37], v[16:31]
	ds_read_b64_tr_b16 v[46:47], v171 offset:0
	ds_read_b64_tr_b16 v[48:49], v171 offset:1088
	ds_read_b64_tr_b16 v[42:43], v171 offset:64
	ds_read_b64_tr_b16 v[44:45], v171 offset:1152
	ds_read_b64_tr_b16 v[38:39], v171 offset:4352
	ds_read_b64_tr_b16 v[40:41], v171 offset:5440
	ds_read_b64_tr_b16 v[34:35], v171 offset:4416
	ds_read_b64_tr_b16 v[36:37], v171 offset:5504
	s_waitcnt lgkmcnt(0)
	ds_read_b128 v[50:53], v54 offset:128
	s_waitcnt lgkmcnt(0)
	v_mfma_f32_32x32x16_bf16 v[16:31], v[50:53], v[42:45], v[16:31]
	ds_read_b128 v[42:45], v55 offset:128
	v_mfma_f32_32x32x16_bf16 v[0:15], v[50:53], v[46:49], v[0:15]
	s_waitcnt lgkmcnt(0)
	v_mfma_f32_32x32x16_bf16 v[0:15], v[42:45], v[38:41], v[0:15]
	v_mfma_f32_32x32x16_bf16 v[16:31], v[42:45], v[34:37], v[16:31]
	ds_read_b64_tr_b16 v[46:47], v172 offset:0
	ds_read_b64_tr_b16 v[48:49], v172 offset:1088
	ds_read_b64_tr_b16 v[42:43], v172 offset:64
	ds_read_b64_tr_b16 v[44:45], v172 offset:1152
	ds_read_b64_tr_b16 v[38:39], v172 offset:4352
	ds_read_b64_tr_b16 v[40:41], v172 offset:5440
	ds_read_b64_tr_b16 v[34:35], v172 offset:4416
	ds_read_b64_tr_b16 v[36:37], v172 offset:5504
	s_waitcnt lgkmcnt(0)
	ds_read_b128 v[50:53], v54 offset:192
	s_waitcnt lgkmcnt(0)
	v_mfma_f32_32x32x16_bf16 v[16:31], v[50:53], v[42:45], v[16:31]
	ds_read_b128 v[42:45], v55 offset:192
	s_waitcnt lgkmcnt(0)
	s_barrier
	v_mfma_f32_32x32x16_bf16 v[0:15], v[50:53], v[46:49], v[0:15]
	v_mfma_f32_32x32x16_bf16 v[0:15], v[42:45], v[38:41], v[0:15]
	v_mfma_f32_32x32x16_bf16 v[16:31], v[42:45], v[34:37], v[16:31]
	s_nop 11
	ds_write2_b32 v175, v0, v16 offset1:32
	ds_write2_b32 v175, v1, v17 offset0:132 offset1:164
	v_add_u32_e32 v0, 0x400, v175
	ds_write2_b32 v0, v2, v18 offset0:8 offset1:40
	ds_write2_b32 v0, v3, v19 offset0:140 offset1:172
	v_add_u32_e32 v0, 0x1000, v175
	ds_write2_b32 v0, v4, v20 offset0:32 offset1:64
	ds_write2_b32 v0, v5, v21 offset0:164 offset1:196
	v_add_u32_e32 v0, 0x1400, v175
	ds_write2_b32 v0, v6, v22 offset0:40 offset1:72
	ds_write2_b32 v0, v7, v23 offset0:172 offset1:204
	v_add_u32_e32 v0, 0x2000, v175
	ds_write2_b32 v0, v8, v24 offset0:64 offset1:96
	ds_write2_b32 v0, v9, v25 offset0:196 offset1:228
	v_add_u32_e32 v0, 0x2400, v175
	ds_write2_b32 v0, v10, v26 offset0:72 offset1:104
	ds_write2_b32 v0, v11, v27 offset0:204 offset1:236
	v_add_u32_e32 v0, 0x3000, v175
	ds_write2_b32 v0, v12, v28 offset0:96 offset1:128
	v_add_u32_e32 v0, 0x3200, v175
	ds_write2_b32 v0, v13, v29 offset0:100 offset1:132
	v_add_u32_e32 v0, 0x3400, v175
	ds_write2_b32 v0, v14, v30 offset0:104 offset1:136
	v_add_u32_e32 v0, 0x3600, v175
	ds_write2_b32 v0, v15, v31 offset0:108 offset1:140
	v_lshl_add_u64 v[0:1], v[88:89], 0, s[8:9]
	v_lshl_add_u64 v[24:25], s[0:1], 0, v[90:91]
	s_waitcnt lgkmcnt(0)
	s_barrier
	global_load_dwordx4 v[12:15], v[0:1], off offset:16
	global_load_dwordx4 v[16:19], v[0:1], off
	ds_read_b128 v[46:49], v176
	ds_read_b128 v[50:53], v176 offset:16
	ds_read_b128 v[54:57], v176 offset:2112
	ds_read_b128 v[58:61], v176 offset:2128
	ds_read_b128 v[62:65], v176 offset:4224
	ds_read_b128 v[66:69], v176 offset:4240
	ds_read_b128 v[70:73], v176 offset:6336
	ds_read_b128 v[74:77], v176 offset:6352
	s_waitcnt lgkmcnt(6)
	v_add_f32_e32 v34, 0, v46
	v_add_f32_e32 v34, v47, v34
	v_add_f32_e32 v34, v48, v34
	v_add_f32_e32 v34, v49, v34
	v_add_f32_e32 v34, v50, v34
	v_add_f32_e32 v34, v51, v34
	v_add_f32_e32 v34, v52, v34
	v_add_f32_e32 v34, v53, v34
	s_waitcnt lgkmcnt(4)
	v_add_f32_e32 v35, 0, v54
	v_add_f32_e32 v35, v55, v35
	v_add_f32_e32 v35, v56, v35
	v_add_f32_e32 v35, v57, v35
	v_add_f32_e32 v35, v58, v35
	v_add_f32_e32 v35, v59, v35
	v_add_f32_e32 v35, v60, v35
	v_add_f32_e32 v35, v61, v35
	s_waitcnt lgkmcnt(2)
	v_add_f32_e32 v36, 0, v62
	v_add_f32_e32 v36, v63, v36
	v_add_f32_e32 v36, v64, v36
	v_add_f32_e32 v36, v65, v36
	v_add_f32_e32 v36, v66, v36
	v_add_f32_e32 v36, v67, v36
	v_add_f32_e32 v36, v68, v36
	v_add_f32_e32 v36, v69, v36
	s_waitcnt lgkmcnt(0)
	v_add_f32_e32 v37, 0, v70
	v_add_f32_e32 v37, v71, v37
	v_add_f32_e32 v37, v72, v37
	v_add_f32_e32 v37, v73, v37
	v_add_f32_e32 v37, v74, v37
	v_add_f32_e32 v37, v75, v37
	v_add_f32_e32 v37, v76, v37
	v_add_f32_e32 v37, v77, v37
	ds_bpermute_b32 v38, v233, v34
	ds_bpermute_b32 v39, v233, v35
	ds_bpermute_b32 v40, v233, v36
	ds_bpermute_b32 v30, v233, v37
	s_waitcnt lgkmcnt(3)
	v_add_f32_e32 v34, v34, v38
	s_waitcnt lgkmcnt(2)
	v_add_f32_e32 v35, v35, v39
	s_waitcnt lgkmcnt(1)
	v_add_f32_e32 v36, v36, v40
	s_waitcnt lgkmcnt(0)
	v_add_f32_e32 v37, v37, v30
	ds_bpermute_b32 v38, v232, v34
	ds_bpermute_b32 v39, v232, v35
	ds_bpermute_b32 v40, v232, v36
	ds_bpermute_b32 v30, v232, v37
	s_waitcnt lgkmcnt(3)
	v_add_f32_e32 v34, v34, v38
	s_waitcnt lgkmcnt(2)
	v_add_f32_e32 v35, v35, v39
	s_waitcnt lgkmcnt(1)
	v_add_f32_e32 v36, v36, v40
	s_waitcnt lgkmcnt(0)
	v_add_f32_e32 v37, v37, v30
	ds_bpermute_b32 v38, v231, v34
	ds_bpermute_b32 v39, v231, v35
	ds_bpermute_b32 v40, v231, v36
	ds_bpermute_b32 v30, v231, v37
	s_waitcnt lgkmcnt(3)
	v_add_f32_e32 v34, v34, v38
	s_waitcnt lgkmcnt(2)
	v_add_f32_e32 v35, v35, v39
	s_waitcnt lgkmcnt(1)
	v_add_f32_e32 v36, v36, v40
	s_waitcnt lgkmcnt(0)
	v_add_f32_e32 v37, v37, v30
	ds_bpermute_b32 v38, v230, v34
	ds_bpermute_b32 v39, v230, v35
	ds_bpermute_b32 v40, v230, v36
	ds_bpermute_b32 v30, v230, v37
	s_waitcnt lgkmcnt(3)
	v_add_f32_e32 v34, v34, v38
	s_waitcnt lgkmcnt(2)
	v_add_f32_e32 v35, v35, v39
	s_waitcnt lgkmcnt(1)
	v_add_f32_e32 v36, v36, v40
	s_waitcnt lgkmcnt(0)
	v_add_f32_e32 v37, v37, v30
	v_mul_f32_e32 v38, 0x3c000000, v34
	v_mul_f32_e32 v39, 0x3c000000, v35
	v_mul_f32_e32 v40, 0x3c000000, v36
	v_mul_f32_e32 v30, 0x3c000000, v37
	v_sub_f32_e32 v46, v46, v38
	v_sub_f32_e32 v47, v47, v38
	v_sub_f32_e32 v48, v48, v38
	v_sub_f32_e32 v49, v49, v38
	v_sub_f32_e32 v50, v50, v38
	v_sub_f32_e32 v51, v51, v38
	v_sub_f32_e32 v52, v52, v38
	v_sub_f32_e32 v53, v53, v38
	v_sub_f32_e32 v54, v54, v39
	v_sub_f32_e32 v55, v55, v39
	v_sub_f32_e32 v56, v56, v39
	v_sub_f32_e32 v57, v57, v39
	v_sub_f32_e32 v58, v58, v39
	v_sub_f32_e32 v59, v59, v39
	v_sub_f32_e32 v60, v60, v39
	v_sub_f32_e32 v61, v61, v39
	v_sub_f32_e32 v62, v62, v40
	v_sub_f32_e32 v63, v63, v40
	v_sub_f32_e32 v64, v64, v40
	v_sub_f32_e32 v65, v65, v40
	v_sub_f32_e32 v66, v66, v40
	v_sub_f32_e32 v67, v67, v40
	v_sub_f32_e32 v68, v68, v40
	v_sub_f32_e32 v69, v69, v40
	v_sub_f32_e32 v70, v70, v30
	v_sub_f32_e32 v71, v71, v30
	v_sub_f32_e32 v72, v72, v30
	v_sub_f32_e32 v73, v73, v30
	v_sub_f32_e32 v74, v74, v30
	v_sub_f32_e32 v75, v75, v30
	v_sub_f32_e32 v76, v76, v30
	v_sub_f32_e32 v77, v77, v30
	v_mul_f32_e32 v34, v47, v47
	v_fmac_f32_e32 v34, v46, v46
	v_mul_f32_e32 v35, v55, v55
	v_fmac_f32_e32 v35, v54, v54
	v_mul_f32_e32 v36, v63, v63
	v_fmac_f32_e32 v36, v62, v62
	v_mul_f32_e32 v37, v71, v71
	v_fmac_f32_e32 v37, v70, v70
	v_mul_f32_e32 v38, v48, v48
	v_mul_f32_e32 v39, v56, v56
	v_mul_f32_e32 v40, v64, v64
	v_mul_f32_e32 v30, v72, v72
	v_add_f32_e32 v34, v38, v34
	v_add_f32_e32 v35, v39, v35
	v_add_f32_e32 v36, v40, v36
	v_add_f32_e32 v37, v30, v37
	v_mul_f32_e32 v38, v49, v49
	v_mul_f32_e32 v39, v57, v57
	v_mul_f32_e32 v40, v65, v65
	v_mul_f32_e32 v30, v73, v73
	v_add_f32_e32 v34, v38, v34
	v_add_f32_e32 v35, v39, v35
	v_add_f32_e32 v36, v40, v36
	v_add_f32_e32 v37, v30, v37
	v_mul_f32_e32 v38, v50, v50
	v_mul_f32_e32 v39, v58, v58
	v_mul_f32_e32 v40, v66, v66
	v_mul_f32_e32 v30, v74, v74
	v_add_f32_e32 v34, v38, v34
	v_add_f32_e32 v35, v39, v35
	v_add_f32_e32 v36, v40, v36
	v_add_f32_e32 v37, v30, v37
	v_mul_f32_e32 v38, v51, v51
	v_mul_f32_e32 v39, v59, v59
	v_mul_f32_e32 v40, v67, v67
	v_mul_f32_e32 v30, v75, v75
	v_add_f32_e32 v34, v38, v34
	v_add_f32_e32 v35, v39, v35
	v_add_f32_e32 v36, v40, v36
	v_add_f32_e32 v37, v30, v37
	v_mul_f32_e32 v38, v52, v52
	v_mul_f32_e32 v39, v60, v60
	v_mul_f32_e32 v40, v68, v68
	v_mul_f32_e32 v30, v76, v76
	v_add_f32_e32 v34, v38, v34
	v_add_f32_e32 v35, v39, v35
	v_add_f32_e32 v36, v40, v36
	v_add_f32_e32 v37, v30, v37
	v_mul_f32_e32 v38, v53, v53
	v_mul_f32_e32 v39, v61, v61
	v_mul_f32_e32 v40, v69, v69
	v_mul_f32_e32 v30, v77, v77
	v_add_f32_e32 v34, v38, v34
	v_add_f32_e32 v35, v39, v35
	v_add_f32_e32 v36, v40, v36
	v_add_f32_e32 v37, v30, v37
	ds_bpermute_b32 v38, v233, v34
	ds_bpermute_b32 v39, v233, v35
	ds_bpermute_b32 v40, v233, v36
	ds_bpermute_b32 v30, v233, v37
	s_waitcnt lgkmcnt(3)
	v_add_f32_e32 v34, v34, v38
	s_waitcnt lgkmcnt(2)
	v_add_f32_e32 v35, v35, v39
	s_waitcnt lgkmcnt(1)
	v_add_f32_e32 v36, v36, v40
	s_waitcnt lgkmcnt(0)
	v_add_f32_e32 v37, v37, v30
	ds_bpermute_b32 v38, v232, v34
	ds_bpermute_b32 v39, v232, v35
	ds_bpermute_b32 v40, v232, v36
	ds_bpermute_b32 v30, v232, v37
	s_waitcnt lgkmcnt(3)
	v_add_f32_e32 v34, v34, v38
	s_waitcnt lgkmcnt(2)
	v_add_f32_e32 v35, v35, v39
	s_waitcnt lgkmcnt(1)
	v_add_f32_e32 v36, v36, v40
	s_waitcnt lgkmcnt(0)
	v_add_f32_e32 v37, v37, v30
	ds_bpermute_b32 v38, v231, v34
	ds_bpermute_b32 v39, v231, v35
	ds_bpermute_b32 v40, v231, v36
	ds_bpermute_b32 v30, v231, v37
	s_waitcnt lgkmcnt(3)
	v_add_f32_e32 v34, v34, v38
	s_waitcnt lgkmcnt(2)
	v_add_f32_e32 v35, v35, v39
	s_waitcnt lgkmcnt(1)
	v_add_f32_e32 v36, v36, v40
	s_waitcnt lgkmcnt(0)
	v_add_f32_e32 v37, v37, v30
	ds_bpermute_b32 v38, v230, v34
	ds_bpermute_b32 v39, v230, v35
	ds_bpermute_b32 v40, v230, v36
	ds_bpermute_b32 v30, v230, v37
	s_waitcnt lgkmcnt(3)
	v_add_f32_e32 v34, v34, v38
	s_waitcnt lgkmcnt(2)
	v_add_f32_e32 v35, v35, v39
	s_waitcnt lgkmcnt(1)
	v_add_f32_e32 v36, v36, v40
	s_waitcnt lgkmcnt(0)
	v_add_f32_e32 v37, v37, v30
	v_fmamk_f32 v34, v34, 0x3c000000, v218
	v_cmp_gt_f32_e32 vcc, s18, v34
	v_mul_f32_e32 v38, 0x4b800000, v34
	s_nop 0
	v_cndmask_b32_e32 v34, v34, v38, vcc
	v_rsq_f32_e32 v34, v34
	s_nop 0
	v_mul_f32_e32 v38, 0x45800000, v34
	v_cndmask_b32_e32 v34, v34, v38, vcc
	v_fmamk_f32 v35, v35, 0x3c000000, v218
	v_cmp_gt_f32_e32 vcc, s18, v35
	v_mul_f32_e32 v39, 0x4b800000, v35
	s_nop 0
	v_cndmask_b32_e32 v35, v35, v39, vcc
	v_rsq_f32_e32 v35, v35
	s_nop 0
	v_mul_f32_e32 v39, 0x45800000, v35
	v_cndmask_b32_e32 v35, v35, v39, vcc
	v_fmamk_f32 v36, v36, 0x3c000000, v218
	v_cmp_gt_f32_e32 vcc, s18, v36
	v_mul_f32_e32 v40, 0x4b800000, v36
	s_nop 0
	v_cndmask_b32_e32 v36, v36, v40, vcc
	v_rsq_f32_e32 v36, v36
	s_nop 0
	v_mul_f32_e32 v40, 0x45800000, v36
	v_cndmask_b32_e32 v36, v36, v40, vcc
	v_fmamk_f32 v37, v37, 0x3c000000, v218
	v_cmp_gt_f32_e32 vcc, s18, v37
	v_mul_f32_e32 v30, 0x4b800000, v37
	s_nop 0
	v_cndmask_b32_e32 v37, v37, v30, vcc
	v_rsq_f32_e32 v37, v37
	s_nop 0
	v_mul_f32_e32 v30, 0x45800000, v37
	v_cndmask_b32_e32 v37, v37, v30, vcc
	s_waitcnt vmcnt(0)
	v_mul_f32_e32 v46, v46, v34
	v_mul_f32_e32 v46, v16, v46
	v_mul_f32_e32 v47, v47, v34
	v_mul_f32_e32 v47, v17, v47
	v_mul_f32_e32 v48, v48, v34
	v_mul_f32_e32 v48, v18, v48
	v_mul_f32_e32 v49, v49, v34
	v_mul_f32_e32 v49, v19, v49
	v_mul_f32_e32 v50, v50, v34
	v_mul_f32_e32 v50, v12, v50
	v_mul_f32_e32 v51, v51, v34
	v_mul_f32_e32 v51, v13, v51
	v_mul_f32_e32 v52, v52, v34
	v_mul_f32_e32 v52, v14, v52
	v_mul_f32_e32 v53, v53, v34
	v_mul_f32_e32 v53, v15, v53
	v_lshlrev_b32_e32 v26, 16, v242
	v_and_b32_e32 v27, 0xffff0000, v242
	v_mul_f32_e32 v26, v46, v26
	v_mul_f32_e32 v27, v47, v27
	v_cvt_pk_bf16_f32 v0, v26, v27
	v_lshlrev_b32_e32 v26, 16, v243
	v_and_b32_e32 v27, 0xffff0000, v243
	v_mul_f32_e32 v26, v48, v26
	v_mul_f32_e32 v27, v49, v27
	v_cvt_pk_bf16_f32 v1, v26, v27
	v_lshlrev_b32_e32 v26, 16, v244
	v_and_b32_e32 v27, 0xffff0000, v244
	v_mul_f32_e32 v26, v50, v26
	v_mul_f32_e32 v27, v51, v27
	v_cvt_pk_bf16_f32 v2, v26, v27
	v_lshlrev_b32_e32 v26, 16, v245
	v_and_b32_e32 v27, 0xffff0000, v245
	v_mul_f32_e32 v26, v52, v26
	v_mul_f32_e32 v27, v53, v27
	v_cvt_pk_bf16_f32 v3, v26, v27
	v_mul_f32_e32 v54, v54, v35
	v_mul_f32_e32 v54, v16, v54
	v_mul_f32_e32 v55, v55, v35
	v_mul_f32_e32 v55, v17, v55
	v_mul_f32_e32 v56, v56, v35
	v_mul_f32_e32 v56, v18, v56
	v_mul_f32_e32 v57, v57, v35
	v_mul_f32_e32 v57, v19, v57
	v_mul_f32_e32 v58, v58, v35
	v_mul_f32_e32 v58, v12, v58
	v_mul_f32_e32 v59, v59, v35
	v_mul_f32_e32 v59, v13, v59
	v_mul_f32_e32 v60, v60, v35
	v_mul_f32_e32 v60, v14, v60
	v_mul_f32_e32 v61, v61, v35
	v_mul_f32_e32 v61, v15, v61
	v_lshlrev_b32_e32 v26, 16, v246
	v_and_b32_e32 v27, 0xffff0000, v246
	v_mul_f32_e32 v26, v54, v26
	v_mul_f32_e32 v27, v55, v27
	v_cvt_pk_bf16_f32 v4, v26, v27
	v_lshlrev_b32_e32 v26, 16, v247
	v_and_b32_e32 v27, 0xffff0000, v247
	v_mul_f32_e32 v26, v56, v26
	v_mul_f32_e32 v27, v57, v27
	v_cvt_pk_bf16_f32 v5, v26, v27
	v_lshlrev_b32_e32 v26, 16, v248
	v_and_b32_e32 v27, 0xffff0000, v248
	v_mul_f32_e32 v26, v58, v26
	v_mul_f32_e32 v27, v59, v27
	v_cvt_pk_bf16_f32 v6, v26, v27
	v_lshlrev_b32_e32 v26, 16, v249
	v_and_b32_e32 v27, 0xffff0000, v249
	v_mul_f32_e32 v26, v60, v26
	v_mul_f32_e32 v27, v61, v27
	v_cvt_pk_bf16_f32 v7, v26, v27
	v_mul_f32_e32 v62, v62, v36
	v_mul_f32_e32 v62, v16, v62
	v_mul_f32_e32 v63, v63, v36
	v_mul_f32_e32 v63, v17, v63
	v_mul_f32_e32 v64, v64, v36
	v_mul_f32_e32 v64, v18, v64
	v_mul_f32_e32 v65, v65, v36
	v_mul_f32_e32 v65, v19, v65
	v_mul_f32_e32 v66, v66, v36
	v_mul_f32_e32 v66, v12, v66
	v_mul_f32_e32 v67, v67, v36
	v_mul_f32_e32 v67, v13, v67
	v_mul_f32_e32 v68, v68, v36
	v_mul_f32_e32 v68, v14, v68
	v_mul_f32_e32 v69, v69, v36
	v_mul_f32_e32 v69, v15, v69
	v_lshlrev_b32_e32 v26, 16, v78
	v_and_b32_e32 v27, 0xffff0000, v78
	v_mul_f32_e32 v26, v62, v26
	v_mul_f32_e32 v27, v63, v27
	v_cvt_pk_bf16_f32 v8, v26, v27
	v_lshlrev_b32_e32 v26, 16, v79
	v_and_b32_e32 v27, 0xffff0000, v79
	v_mul_f32_e32 v26, v64, v26
	v_mul_f32_e32 v27, v65, v27
	v_cvt_pk_bf16_f32 v9, v26, v27
	v_lshlrev_b32_e32 v26, 16, v80
	v_and_b32_e32 v27, 0xffff0000, v80
	v_mul_f32_e32 v26, v66, v26
	v_mul_f32_e32 v27, v67, v27
	v_cvt_pk_bf16_f32 v10, v26, v27
	v_lshlrev_b32_e32 v26, 16, v81
	v_and_b32_e32 v27, 0xffff0000, v81
	v_mul_f32_e32 v26, v68, v26
	v_mul_f32_e32 v27, v69, v27
	v_cvt_pk_bf16_f32 v11, v26, v27
	v_mul_f32_e32 v70, v70, v37
	v_mul_f32_e32 v70, v16, v70
	v_mul_f32_e32 v71, v71, v37
	v_mul_f32_e32 v71, v17, v71
	v_mul_f32_e32 v72, v72, v37
	v_mul_f32_e32 v72, v18, v72
	v_mul_f32_e32 v73, v73, v37
	v_mul_f32_e32 v73, v19, v73
	v_mul_f32_e32 v74, v74, v37
	v_mul_f32_e32 v74, v12, v74
	v_mul_f32_e32 v75, v75, v37
	v_mul_f32_e32 v75, v13, v75
	v_mul_f32_e32 v76, v76, v37
	v_mul_f32_e32 v76, v14, v76
	v_mul_f32_e32 v77, v77, v37
	v_mul_f32_e32 v77, v15, v77
	v_lshlrev_b32_e32 v26, 16, v250
	v_and_b32_e32 v27, 0xffff0000, v250
	v_mul_f32_e32 v26, v70, v26
	v_mul_f32_e32 v27, v71, v27
	v_cvt_pk_bf16_f32 v20, v26, v27
	v_lshlrev_b32_e32 v26, 16, v251
	v_and_b32_e32 v27, 0xffff0000, v251
	v_mul_f32_e32 v26, v72, v26
	v_mul_f32_e32 v27, v73, v27
	v_cvt_pk_bf16_f32 v21, v26, v27
	v_lshlrev_b32_e32 v26, 16, v252
	v_and_b32_e32 v27, 0xffff0000, v252
	v_mul_f32_e32 v26, v74, v26
	v_mul_f32_e32 v27, v75, v27
	v_cvt_pk_bf16_f32 v22, v26, v27
	v_lshlrev_b32_e32 v26, 16, v253
	v_and_b32_e32 v27, 0xffff0000, v253
	v_mul_f32_e32 v26, v76, v26
	v_mul_f32_e32 v27, v77, v27
	v_cvt_pk_bf16_f32 v23, v26, v27
	v_lshlrev_b64 v[26:27], 12, v[24:25]
	v_mov_b32_e32 v28, v26
	v_mov_b32_e32 v29, v27
	v_lshl_add_u64 v[28:29], s[4:5], 0, v[28:29]
	v_lshl_add_u64 v[28:29], v[28:29], 0, s[88:89]
	v_lshl_add_u64 v[28:29], v[28:29], 0, v[32:33]
	v_add_co_u32_e32 v28, vcc, s24, v28
	s_nop 1
	v_addc_co_u32_e32 v29, vcc, 0, v29, vcc
	global_store_dwordx4 v[28:29], v[0:3], off offset:3072
	v_or_b32_e32 v28, 0x4000, v26
	v_mov_b32_e32 v29, v27
	v_lshl_add_u64 v[28:29], s[4:5], 0, v[28:29]
	v_lshl_add_u64 v[28:29], v[28:29], 0, s[88:89]
	v_lshl_add_u64 v[28:29], v[28:29], 0, v[32:33]
	v_add_co_u32_e32 v28, vcc, s24, v28
	s_nop 1
	v_addc_co_u32_e32 v29, vcc, 0, v29, vcc
	global_store_dwordx4 v[28:29], v[4:7], off offset:3072
	v_or_b32_e32 v28, 0x8000, v26
	v_mov_b32_e32 v29, v27
	v_lshl_add_u64 v[28:29], s[4:5], 0, v[28:29]
	v_lshl_add_u64 v[28:29], v[28:29], 0, s[88:89]
	v_lshl_add_u64 v[28:29], v[28:29], 0, v[32:33]
	v_add_co_u32_e32 v28, vcc, s24, v28
	s_nop 1
	v_addc_co_u32_e32 v29, vcc, 0, v29, vcc
	global_store_dwordx4 v[28:29], v[8:11], off offset:3072
	v_or_b32_e32 v28, 0xc000, v26
	v_mov_b32_e32 v29, v27
	v_lshl_add_u64 v[28:29], s[4:5], 0, v[28:29]
	v_lshl_add_u64 v[28:29], v[28:29], 0, s[88:89]
	v_lshl_add_u64 v[28:29], v[28:29], 0, v[32:33]
	v_add_co_u32_e32 v28, vcc, s24, v28
	s_nop 1
	v_addc_co_u32_e32 v29, vcc, 0, v29, vcc
	global_store_dwordx4 v[28:29], v[20:23], off offset:3072
	s_cbranch_scc1 .LBB0_802

	.amdhsa_kernel _Z4mega6Params
		.amdhsa_group_segment_fixed_size 0
		.amdhsa_private_segment_fixed_size 0
		.amdhsa_kernarg_size 448
		.amdhsa_user_sgpr_count 2
		.amdhsa_user_sgpr_dispatch_ptr 0
		.amdhsa_user_sgpr_queue_ptr 0
		.amdhsa_user_sgpr_kernarg_segment_ptr 1
		.amdhsa_user_sgpr_dispatch_id 0
		.amdhsa_user_sgpr_kernarg_preload_length 0
		.amdhsa_user_sgpr_kernarg_preload_offset 0
		.amdhsa_user_sgpr_private_segment_size 0
		.amdhsa_uses_dynamic_stack 0
		.amdhsa_enable_private_segment 0
		.amdhsa_system_sgpr_workgroup_id_x 1
		.amdhsa_system_sgpr_workgroup_id_y 0
		.amdhsa_system_sgpr_workgroup_id_z 0
		.amdhsa_system_sgpr_workgroup_info 0
		.amdhsa_system_vgpr_workitem_id 2
		.amdhsa_next_free_vgpr 256
		.amdhsa_next_free_sgpr 102
		.amdhsa_accum_offset 256
		.amdhsa_reserve_vcc 1
		.amdhsa_float_round_mode_32 0
		.amdhsa_float_round_mode_16_64 0
		.amdhsa_float_denorm_mode_32 3
		.amdhsa_float_denorm_mode_16_64 3
		.amdhsa_dx10_clamp 1
		.amdhsa_ieee_mode 1
		.amdhsa_fp16_overflow 0
		.amdhsa_tg_split 0
		.amdhsa_exception_fp_ieee_invalid_op 0
		.amdhsa_exception_fp_denorm_src 0
		.amdhsa_exception_fp_ieee_div_zero 0
		.amdhsa_exception_fp_ieee_overflow 0
		.amdhsa_exception_fp_ieee_underflow 0
		.amdhsa_exception_fp_ieee_inexact 0
		.amdhsa_exception_int_div_zero 0
	.end_amdhsa_kernel

amdhsa.kernels:
  - .agpr_count:     0
    .args:
      - .offset:         0
        .size:           192
        .value_kind:     by_value
      - .offset:         192
        .size:           4
        .value_kind:     hidden_block_count_x
      - .offset:         196
        .size:           4
        .value_kind:     hidden_block_count_y
      - .offset:         200
        .size:           4
        .value_kind:     hidden_block_count_z
      - .offset:         204
        .size:           2
        .value_kind:     hidden_group_size_x
      - .offset:         206
        .size:           2
        .value_kind:     hidden_group_size_y
      - .offset:         208
        .size:           2
        .value_kind:     hidden_group_size_z
      - .offset:         210
        .size:           2
        .value_kind:     hidden_remainder_x
      - .offset:         212
        .size:           2
        .value_kind:     hidden_remainder_y
      - .offset:         214
        .size:           2
        .value_kind:     hidden_remainder_z
      - .offset:         232
        .size:           8
        .value_kind:     hidden_global_offset_x
      - .offset:         240
        .size:           8
        .value_kind:     hidden_global_offset_y
      - .offset:         248
        .size:           8
        .value_kind:     hidden_global_offset_z
      - .offset:         256
        .size:           2
        .value_kind:     hidden_grid_dims
      - .offset:         280
        .size:           8
        .value_kind:     hidden_multigrid_sync_arg
      - .offset:         312
        .size:           4
        .value_kind:     hidden_dynamic_lds_size
    .group_segment_fixed_size: 0
    .kernarg_segment_align: 8
    .kernarg_segment_size: 448
    .language:       OpenCL C
    .language_version:
      - 2
      - 0
    .max_flat_workgroup_size: 512
    .name:           _Z4mega6Params
    .private_segment_fixed_size: 0
    .sgpr_count:     108
    .sgpr_spill_count: 125
    .symbol:         _Z4mega6Params.kd
    .uniform_work_group_size: 1
    .uses_dynamic_stack: false
    .vgpr_count:     256
    .vgpr_spill_count: 0
    .wavefront_size: 64
